# q9 + attention tile loops: next-tile K/V loads issued before the per-tile barrier
# speedup vs baseline: 1.0447x; 1.0107x over previous
; #define LAS __attribute__((address_space(3)))
; template <int BR>
; DI void attn_branch(const AttnCtx& c, unsigned long long tmask, const bf16_t* kbase, size_t kpitch, const bf16_t* vbase, size_t vpitch, f32x16 (&o)[2], float& lsum) {
;     ...
;         LAS bf16_t* Ks = (LAS bf16_t*)(c.lds + AT_BUF + (it & 1) * AT_BUFSZ); LAS bf16_t* Vs = (LAS bf16_t*)(c.lds + AT_BUF + (it & 1) * AT_BUFSZ + AT_VOFF);
;         *(LAS u32x4*)(Ks + rowi * 72 + seg * 8) = kr;
;         if (BR != 0) { *(LAS u32x2*)(Vs + rowi * 68 + seg * 8) = (u32x2){vr.x, vr.y}; *(LAS u32x2*)(Vs + rowi * 68 + seg * 8 + 4) = (u32x2){vr.z, vr.w}; }
;         __syncthreads();
;         const int jc = j; const bool more = m != 0ull;
;         if (more) { j = __ffsll((long long)m) - 1; m &= m - 1; kr = *(const u32x4*)(kg + (size_t)j * 64 * kpitch); if (BR != 0) vr = *(const u32x4*)(vg + j * 64); }
.LBB0_321:
	s_and_b64 s[4:5], s[0:1], exec
	s_cselect_b32 s4, 0x4800, 0
	s_add_i32 s15, s4, 0
	s_add_i32 s15, s15, 0x10600
	v_add3_u32 v32, s15, v187, v72
	s_waitcnt vmcnt(1)
	ds_write_b128 v32, v[64:67]
	v_add_u32_e32 v32, s15, v196
	s_movk_i32 s4, 0x2400
	s_cmp_eq_u64 s[8:9], 0
	v_add3_u32 v32, v32, v72, s4
	s_cselect_b64 s[4:5], -1, 0
	s_and_b64 vcc, exec, s[4:5]
	s_mov_b64 s[6:7], 0
	s_waitcnt vmcnt(0)
	ds_write2_b64 v32, v[68:69], v[70:71] offset1:1
	s_cbranch_vccnz .LBB0_323
	s_ff1_i32_b64 s14, s[8:9]
	s_add_u32 s6, s8, -1
	v_readlane_b32 s16, v247, 34
	s_addc_u32 s7, s9, -1
	v_readlane_b32 s17, v247, 35
	s_lshl_b32 s16, s14, 13
	s_mov_b32 s13, s17
	v_lshl_add_u64 v[32:33], v[74:75], 0, s[16:17]
	s_lshl_b32 s16, s14, 7
	v_lshl_add_u64 v[34:35], v[76:77], 0, s[16:17]
	global_load_dwordx4 v[64:67], v[32:33], off
	global_load_dwordx4 v[68:71], v[34:35], off
	v_readlane_b32 s18, v247, 36
	v_readlane_b32 s19, v247, 37
	v_writelane_b32 v247, s12, 34
	s_and_b64 s[6:7], s[6:7], s[8:9]
	s_nop 0
	v_writelane_b32 v247, s13, 35
	v_writelane_b32 v247, s14, 36
	v_writelane_b32 v247, s15, 37
.LBB0_323:
	s_waitcnt lgkmcnt(0)
	s_barrier
	s_lshl_b32 s16, s12, 6
	s_add_i32 s8, s16, 64
	v_cmp_le_u32_e32 vcc, s8, v85
	s_and_b64 s[8:9], s[2:3], vcc
	s_and_saveexec_b64 s[10:11], s[8:9]
	s_xor_b64 s[8:9], exec, s[10:11]
	s_cbranch_execnz .LBB0_326
	s_andn2_saveexec_b64 s[8:9], s[8:9]
	s_cbranch_execnz .LBB0_335

; #define LAS __attribute__((address_space(3)))
; template <int BR>
; DI void attn_branch(const AttnCtx& c, unsigned long long tmask, const bf16_t* kbase, size_t kpitch, const bf16_t* vbase, size_t vpitch, f32x16 (&o)[2], float& lsum) {
;     ...
;         LAS bf16_t* Ks = (LAS bf16_t*)(c.lds + AT_BUF + (it & 1) * AT_BUFSZ); LAS bf16_t* Vs = (LAS bf16_t*)(c.lds + AT_BUF + (it & 1) * AT_BUFSZ + AT_VOFF);
;         *(LAS u32x4*)(Ks + rowi * 72 + seg * 8) = kr;
;         if (BR != 0) { *(LAS u32x2*)(Vs + rowi * 68 + seg * 8) = (u32x2){vr.x, vr.y}; *(LAS u32x2*)(Vs + rowi * 68 + seg * 8 + 4) = (u32x2){vr.z, vr.w}; }
;         __syncthreads();
;         const int jc = j; const bool more = m != 0ull;
;         if (more) { j = __ffsll((long long)m) - 1; m &= m - 1; kr = *(const u32x4*)(kg + (size_t)j * 64 * kpitch); if (BR != 0) vr = *(const u32x4*)(vg + j * 64); }
;         bool mine = true;
;         if (BR == 2) mine = (c.mymask >> jc) & 1ull;
;         const bool wave_on = (BR == 2 ? (__ballot(mine) != 0ull) : true) && !c.nocompute;
;         if (wave_on) {
;             const float sbias = (BR == 2 && !mine) ? -1e30f : 0.f;
;             bool interior;
;             if (BR <= 1) interior = jc * 64 + 64 <= c.ncvmin;
;             else if (BR == 2) interior = jc * 64 + 63 <= c.tw;
;             else interior = (jc * 64 + 63 <= c.tw) && (jc * 64 > c.tw + 31 - 512);
;             if (interior) {
;                 f32x16 s0, s1;
; #pragma unroll
;                 for (int i = 0; i < 16; ++i) { s0[i] = sbias; s1[i] = sbias; }
; #pragma unroll
;                 for (int st = 0; st < 4; ++st) {
;                     const bf16x8 kf0 = *(const LAS bf16x8*)(Ks + c.qi * 72 + 16 * st + 8 * c.hi), kf1 = *(const LAS bf16x8*)(Ks + (32 + c.qi) * 72 + 16 * st + 8 * c.hi);
;                     s0 = MFMA32(kf0, c.q[st], s0); s1 = MFMA32(kf1, c.q[st], s1);
;                 }
;                 float p0[16], p1[16];
; #pragma unroll
;                 for (int i = 0; i < 16; ++i) { p0[i] = __builtin_amdgcn_exp2f(s0[i]); p1[i] = __builtin_amdgcn_exp2f(s1[i]); }
;                 {
;                     float l0 = 0.f, l1 = 0.f;
; #pragma unroll
;                     for (int i = 0; i < 16; ++i) { l0 += p0[i]; l1 += p1[i]; }
;                     lsum += l0 + l1;
;                 }
;                 if (BR == 1) {
; #pragma unroll
;                     for (int gq = 0; gq < 4; ++gq) {
.LBB0_375:
	s_and_b64 s[6:7], s[4:5], exec
	s_cselect_b32 s6, 0x4800, 0
	s_add_i32 s14, s6, 0
	s_add_i32 s14, s14, 0x10600
	s_waitcnt vmcnt(3)
	v_add3_u32 v64, s14, v187, v108
	s_waitcnt vmcnt(1)
	ds_write_b128 v64, v[96:99]
	v_add_u32_e32 v64, s14, v196
	s_movk_i32 s6, 0x2400
	s_cmp_eq_u64 s[0:1], 0
	v_add3_u32 v64, v64, v108, s6
	s_cselect_b64 s[6:7], -1, 0
	s_and_b64 vcc, exec, s[6:7]
	s_mov_b64 s[8:9], 0
	s_waitcnt vmcnt(0)
	ds_write2_b64 v64, v[100:101], v[102:103] offset1:1
	s_cbranch_vccnz .LBB0_377
	v_readlane_b32 s16, v247, 34
	s_ff1_i32_b64 s13, s[0:1]
	v_readlane_b32 s17, v247, 35
	s_add_u32 s8, s0, -1
	s_mov_b32 s21, s17
	s_mul_i32 s20, s13, 0x60c00
	s_addc_u32 s9, s1, -1
	v_lshl_add_u64 v[64:65], v[110:111], 0, s[20:21]
	s_lshl_b32 s20, s13, 7
	v_lshl_add_u64 v[66:67], v[112:113], 0, s[20:21]
	global_load_dwordx4 v[96:99], v[64:65], off offset:1536
	global_load_dwordx4 v[100:103], v[66:67], off
	v_readlane_b32 s18, v247, 36
	v_readlane_b32 s19, v247, 37
	v_writelane_b32 v247, s16, 34
	s_and_b64 s[8:9], s[8:9], s[0:1]
	s_nop 0
	v_writelane_b32 v247, s17, 35
	v_writelane_b32 v247, s18, 36
	v_writelane_b32 v247, s19, 37
.LBB0_377:
	s_waitcnt lgkmcnt(0)
	s_barrier
	v_lshrrev_b64 v[64:65], s10, v[106:107]
	v_and_b32_e32 v64, 1, v64
	v_cmp_eq_u32_e64 s[0:1], 1, v64
	v_cmp_ne_u32_e32 vcc, 0, v64
	s_cbranch_vccz .LBB0_387
	s_lshl_b32 s15, s10, 6
	v_cndmask_b32_e64 v64, v193, 0, s[0:1]
	s_or_b32 s0, s15, 63
	v_cmp_le_i32_e32 vcc, s0, v171
	s_and_saveexec_b64 s[0:1], vcc
	s_xor_b64 s[0:1], exec, s[0:1]
	s_cbranch_execz .LBB0_380
	v_lshlrev_b32_e32 v80, 1, v170
	v_add3_u32 v109, s14, v185, v80
	ds_read_b128 v[116:119], v109 offset:4608
	ds_read_b128 v[120:123], v109
	ds_read_b128 v[124:127], v109 offset:32
	v_mov_b32_e32 v65, v64
	v_mov_b32_e32 v66, v64
	v_mov_b32_e32 v67, v64
	v_mov_b32_e32 v68, v64
	v_mov_b32_e32 v69, v64
	v_mov_b32_e32 v70, v64
	v_mov_b32_e32 v71, v64
	v_mov_b32_e32 v72, v64
	v_mov_b32_e32 v73, v64
	v_mov_b32_e32 v74, v64
	v_mov_b32_e32 v75, v64
	v_mov_b32_e32 v76, v64
	v_mov_b32_e32 v77, v64
	v_mov_b32_e32 v78, v64
	v_mov_b32_e32 v79, v64
	s_waitcnt lgkmcnt(1)
	s_nop 0
	v_mfma_f32_32x32x16_bf16 v[80:95], v[120:123], v[130:133], v[64:79]
	v_mfma_f32_32x32x16_bf16 v[64:79], v[116:119], v[130:133], v[64:79]
	ds_read_b128 v[116:119], v109 offset:4640
	s_waitcnt lgkmcnt(1)
	v_mfma_f32_32x32x16_bf16 v[80:95], v[124:127], v[134:137], v[80:95]
	s_waitcnt lgkmcnt(0)
	v_mfma_f32_32x32x16_bf16 v[64:79], v[116:119], v[134:137], v[64:79]
	ds_read_b128 v[116:119], v109 offset:64
	ds_read_b128 v[120:123], v109 offset:4672
	s_waitcnt lgkmcnt(1)
	v_mfma_f32_32x32x16_bf16 v[80:95], v[116:119], v[138:141], v[80:95]
	s_waitcnt lgkmcnt(0)
	v_mfma_f32_32x32x16_bf16 v[64:79], v[120:123], v[138:141], v[64:79]
	ds_read_b128 v[116:119], v109 offset:96
	ds_read_b128 v[120:123], v109 offset:4704
	s_waitcnt lgkmcnt(1)
	v_mfma_f32_32x32x16_bf16 v[80:95], v[116:119], v[142:145], v[80:95]
	s_waitcnt lgkmcnt(0)
	v_mfma_f32_32x32x16_bf16 v[64:79], v[120:123], v[142:145], v[64:79]
	s_nop 9
	v_exp_f32_e32 v116, v80
	v_exp_f32_e32 v80, v82
	v_exp_f32_e32 v82, v84
	v_exp_f32_e32 v84, v86
	v_exp_f32_e32 v86, v88
	v_exp_f32_e32 v88, v89
	v_exp_f32_e32 v118, v90
	v_exp_f32_e32 v117, v64
	v_exp_f32_e32 v64, v81
	v_exp_f32_e32 v65, v65
	v_exp_f32_e32 v81, v66
	v_exp_f32_e32 v66, v83
	v_exp_f32_e32 v67, v67
	v_exp_f32_e32 v83, v68
	v_exp_f32_e32 v68, v85
	v_exp_f32_e32 v85, v70
	v_exp_f32_e32 v70, v87
	v_exp_f32_e32 v87, v72
	v_exp_f32_e32 v89, v73
	v_pk_add_f32 v[72:73], v[116:117], 0 op_sel_hi:[1,0]
	v_exp_f32_e32 v69, v69
	v_pk_add_f32 v[72:73], v[64:65], v[72:73]
	v_exp_f32_e32 v71, v71
	v_pk_add_f32 v[72:73], v[80:81], v[72:73]
	v_exp_f32_e32 v119, v74
	v_pk_add_f32 v[72:73], v[66:67], v[72:73]
	v_exp_f32_e32 v90, v91
	v_pk_add_f32 v[72:73], v[82:83], v[72:73]
	v_exp_f32_e32 v91, v75
	v_pk_add_f32 v[72:73], v[68:69], v[72:73]
	v_exp_f32_e32 v120, v92
	v_pk_add_f32 v[72:73], v[84:85], v[72:73]
	v_exp_f32_e32 v121, v76
	v_pk_add_f32 v[72:73], v[70:71], v[72:73]
	v_exp_f32_e32 v92, v93
	v_pk_add_f32 v[72:73], v[86:87], v[72:73]
	v_exp_f32_e32 v93, v77
	v_pk_add_f32 v[72:73], v[88:89], v[72:73]
	v_exp_f32_e32 v122, v94
	v_exp_f32_e32 v123, v78
	v_pk_add_f32 v[72:73], v[118:119], v[72:73]
	v_exp_f32_e32 v94, v95
	v_exp_f32_e32 v95, v79
	v_pk_add_f32 v[72:73], v[90:91], v[72:73]
	v_cvt_pk_bf16_f32 v79, v84, v70
	v_pk_add_f32 v[72:73], v[120:121], v[72:73]
	v_cvt_pk_bf16_f32 v70, v120, v92
	v_pk_add_f32 v[72:73], v[92:93], v[72:73]
	v_add3_u32 v92, s14, v186, v170
	v_pk_add_f32 v[72:73], v[122:123], v[72:73]
	v_cvt_pk_bf16_f32 v77, v80, v66
	v_pk_add_f32 v[72:73], v[94:95], v[72:73]
	v_cvt_pk_bf16_f32 v66, v121, v93
	v_add_f32_e32 v72, v72, v73
	v_add_u32_e32 v93, 0x2000, v92
	v_add_f32_e32 v175, v175, v72
	v_cvt_pk_bf16_f32 v76, v116, v64
	v_cvt_pk_bf16_f32 v72, v117, v65
	v_cvt_pk_bf16_f32 v73, v81, v67
	v_cvt_pk_bf16_f32 v78, v82, v68
	v_cvt_pk_bf16_f32 v74, v83, v69
	v_cvt_pk_bf16_f32 v75, v85, v71
	v_cvt_pk_bf16_f32 v68, v86, v88
	v_cvt_pk_bf16_f32 v64, v87, v89
	v_cvt_pk_bf16_f32 v69, v118, v90
	v_cvt_pk_bf16_f32 v65, v119, v91
	ds_read2_b64 v[80:83], v93 offset0:128 offset1:130
	ds_read2_b64 v[84:87], v93 offset0:132 offset1:134
	ds_read2_b64 v[88:91], v93 offset0:136 offset1:138
	s_waitcnt lgkmcnt(2)
	v_mfma_f32_32x32x16_bf16 v[48:63], v[80:83], v[76:79], v[48:63]
	v_add_u32_e32 v92, 0x3000, v92
	v_cvt_pk_bf16_f32 v71, v122, v94
	v_cvt_pk_bf16_f32 v67, v123, v95
	s_waitcnt lgkmcnt(0)
	v_mfma_f32_32x32x16_bf16 v[48:63], v[88:91], v[72:75], v[48:63]
	ds_read2_b64 v[80:83], v92 offset0:160 offset1:162
	ds_read2_b64 v[88:91], v92 offset0:168 offset1:170
	s_waitcnt lgkmcnt(1)
	v_mfma_f32_32x32x16_bf16 v[32:47], v[80:83], v[76:79], v[32:47]
	s_waitcnt lgkmcnt(0)
	v_mfma_f32_32x32x16_bf16 v[32:47], v[88:91], v[72:75], v[32:47]
	ds_read2_b64 v[72:75], v93 offset0:140 offset1:142
	v_mfma_f32_32x32x16_bf16 v[48:63], v[84:87], v[68:71], v[48:63]
	s_waitcnt lgkmcnt(0)
	v_mfma_f32_32x32x16_bf16 v[48:63], v[72:75], v[64:67], v[48:63]
	ds_read2_b64 v[72:75], v92 offset0:164 offset1:166
	ds_read2_b64 v[76:79], v92 offset0:172 offset1:174
	s_waitcnt lgkmcnt(1)
	v_mfma_f32_32x32x16_bf16 v[32:47], v[72:75], v[68:71], v[32:47]
	s_waitcnt lgkmcnt(0)
	v_mfma_f32_32x32x16_bf16 v[32:47], v[76:79], v[64:67], v[32:47]

; #define LAS __attribute__((address_space(3)))
; template <int BR>
; DI void attn_branch(const AttnCtx& c, unsigned long long tmask, const bf16_t* kbase, size_t kpitch, const bf16_t* vbase, size_t vpitch, f32x16 (&o)[2], float& lsum) {
;     ...
;         LAS bf16_t* Ks = (LAS bf16_t*)(c.lds + AT_BUF + (it & 1) * AT_BUFSZ); LAS bf16_t* Vs = (LAS bf16_t*)(c.lds + AT_BUF + (it & 1) * AT_BUFSZ + AT_VOFF);
;         *(LAS u32x4*)(Ks + rowi * 72 + seg * 8) = kr;
;         if (BR != 0) { *(LAS u32x2*)(Vs + rowi * 68 + seg * 8) = (u32x2){vr.x, vr.y}; *(LAS u32x2*)(Vs + rowi * 68 + seg * 8 + 4) = (u32x2){vr.z, vr.w}; }
;         __syncthreads();
;         const int jc = j; const bool more = m != 0ull;
;         if (more) { j = __ffsll((long long)m) - 1; m &= m - 1; kr = *(const u32x4*)(kg + (size_t)j * 64 * kpitch); if (BR != 0) vr = *(const u32x4*)(vg + j * 64); }
;         bool mine = true;
;         if (BR == 2) mine = (c.mymask >> jc) & 1ull;
;         const bool wave_on = (BR == 2 ? (__ballot(mine) != 0ull) : true) && !c.nocompute;
;         if (wave_on) {
;             const float sbias = (BR == 2 && !mine) ? -1e30f : 0.f;
;             bool interior;
;             if (BR <= 1) interior = jc * 64 + 64 <= c.ncvmin;
;             else if (BR == 2) interior = jc * 64 + 63 <= c.tw;
;             else interior = (jc * 64 + 63 <= c.tw) && (jc * 64 > c.tw + 31 - 512);
.LBB0_393:
	s_and_b64 s[4:5], s[2:3], exec
	s_cselect_b32 s4, 0x4800, 0
	s_add_i32 s11, s4, 0
	s_add_i32 s11, s11, 0x10600
	v_add3_u32 v96, s11, v187, v176
	s_waitcnt vmcnt(1)
	ds_write_b128 v96, v[146:149]
	v_add_u32_e32 v96, s11, v196
	s_movk_i32 s4, 0x2400
	s_cmp_eq_u64 s[0:1], 0
	v_add3_u32 v96, v96, v176, s4
	s_cselect_b64 s[4:5], -1, 0
	s_and_b64 vcc, exec, s[4:5]
	s_mov_b64 s[6:7], 0
	s_waitcnt vmcnt(0)
	ds_write2_b64 v96, v[150:151], v[152:153] offset1:1
	s_cbranch_vccnz .LBB0_395
	s_ff1_i32_b64 s10, s[0:1]
	v_readlane_b32 s12, v247, 34
	s_add_u32 s6, s0, -1
	v_readlane_b32 s13, v247, 35
	s_mul_i32 s12, s10, 0x60c00
	s_addc_u32 s7, s1, -1
	v_lshl_add_u64 v[96:97], v[178:179], 0, s[12:13]
	s_lshl_b32 s12, s10, 7
	v_lshl_add_u64 v[98:99], v[180:181], 0, s[12:13]
	global_load_dwordx4 v[146:149], v[96:97], off offset:2048
	global_load_dwordx4 v[150:153], v[98:99], off
	s_mov_b32 s9, s13
	v_readlane_b32 s14, v247, 36
	v_readlane_b32 s15, v247, 37
	v_writelane_b32 v247, s8, 34
	s_and_b64 s[6:7], s[6:7], s[0:1]
	s_nop 0
	v_writelane_b32 v247, s9, 35
	v_writelane_b32 v247, s10, 36
	v_writelane_b32 v247, s11, 37
.LBB0_395:
	s_waitcnt lgkmcnt(0)
	s_barrier
	s_lshl_b32 s12, s8, 6
	s_or_b32 s13, s12, 63
	v_cmp_gt_i32_e32 vcc, s13, v171
	v_cmp_le_i32_e64 s[0:1], s12, v177
	s_or_b64 s[0:1], vcc, s[0:1]
	s_and_saveexec_b64 s[8:9], s[0:1]
	s_xor_b64 s[8:9], exec, s[8:9]
	s_cbranch_execnz .LBB0_398
	s_andn2_saveexec_b64 s[0:1], s[8:9]
	s_cbranch_execnz .LBB0_403
